# swiglu epilogue rstd LDS reads double-buffered over two safe register quads (counted lgkmcnt); K-loop loader VALU eliminated; peeled first iteration
# speedup vs baseline: 1.0124x; 1.0115x over previous
.LBB0_531:
	v_lshl_add_u32 v154, s54, 12, v145
	ds_read_b128 v[96:99], v154
	ds_read_b128 v[234:237], v154 offset:256
	s_waitcnt lgkmcnt(1)
	v_mov_b32_e32 v150, v97
	v_mov_b32_e32 v151, v98
	v_mov_b32_e32 v97, v99
	v_pk_add_f32 v[96:97], v[150:151], v[96:97]
	v_lshl_add_u32 v151, s24, 8, v139
	v_add_f32_e32 v96, v96, v97
	v_fmamk_f32 v96, v96, 0x3a800000, v229
	v_rsq_f32_e32 v150, v96
	ds_read_b128 v[96:99], v154 offset:512
	v_pk_mul_f32 v[128:129], v[128:129], v[150:151] op_sel_hi:[1,0]
	v_pk_mul_f32 v[124:125], v[124:125], v[150:151] op_sel_hi:[1,0]
	s_waitcnt lgkmcnt(1)
	v_mov_b32_e32 v152, v235
	v_mov_b32_e32 v153, v236
	v_mov_b32_e32 v235, v237
	v_pk_add_f32 v[234:235], v[152:153], v[234:235]
	v_pk_mul_f32 v[124:125], v[124:125], v[128:129]
	v_add_f32_e32 v234, v234, v235
	v_fmamk_f32 v234, v234, 0x3a800000, v229
	v_rsq_f32_e32 v148, v234
	ds_read_b128 v[234:237], v154 offset:768
	v_pk_mul_f32 v[128:129], v[128:129], s[68:69] op_sel_hi:[1,0]
	v_pk_mul_f32 v[126:127], v[126:127], v[150:151] op_sel_hi:[1,0]
	v_exp_f32_e32 v128, v128
	v_exp_f32_e32 v129, v129
	s_waitcnt lgkmcnt(1)
	v_mov_b32_e32 v152, v97
	v_mov_b32_e32 v153, v98
	v_mov_b32_e32 v97, v99
	v_pk_add_f32 v[96:97], v[152:153], v[96:97]
	v_pk_add_f32 v[128:129], v[128:129], 1.0 op_sel_hi:[1,0]
	v_add_f32_e32 v96, v96, v97
	v_fmamk_f32 v96, v96, 0x3a800000, v229
	v_rsq_f32_e32 v146, v96
	ds_read_b128 v[96:99], v154 offset:2048
	v_rcp_f32_e32 v128, v128
	v_rcp_f32_e32 v129, v129
	v_pk_mul_f32 v[120:121], v[120:121], v[150:151] op_sel_hi:[1,0]
	v_pk_mul_f32 v[116:117], v[116:117], v[150:151] op_sel_hi:[1,0]
	s_waitcnt lgkmcnt(1)
	v_mov_b32_e32 v152, v235
	v_mov_b32_e32 v153, v236
	v_mov_b32_e32 v235, v237
	v_pk_add_f32 v[234:235], v[152:153], v[234:235]
	v_pk_mul_f32 v[124:125], v[124:125], v[128:129]
	v_add_f32_e32 v234, v234, v235
	v_fmamk_f32 v234, v234, 0x3a800000, v229
	v_rsq_f32_e32 v144, v234
	ds_read_b128 v[234:237], v154 offset:2304
	v_pk_mul_f32 v[128:129], v[130:131], v[150:151] op_sel_hi:[1,0]
	v_pk_mul_f32 v[116:117], v[120:121], v[116:117]
	v_pk_mul_f32 v[126:127], v[128:129], v[126:127]
	v_pk_mul_f32 v[128:129], v[128:129], s[68:69] op_sel_hi:[1,0]
	s_waitcnt lgkmcnt(1)
	v_mov_b32_e32 v152, v97
	v_mov_b32_e32 v153, v98
	v_mov_b32_e32 v97, v99
	v_pk_add_f32 v[96:97], v[152:153], v[96:97]
	v_pk_mul_f32 v[120:121], v[120:121], s[68:69] op_sel_hi:[1,0]
	v_add_f32_e32 v96, v96, v97
	v_fmamk_f32 v96, v96, 0x3a800000, v229
	v_rsq_f32_e32 v142, v96
	ds_read_b128 v[96:99], v154 offset:2560
	v_exp_f32_e32 v128, v128
	v_exp_f32_e32 v129, v129
	v_exp_f32_e32 v120, v120
	v_exp_f32_e32 v121, v121
	s_waitcnt lgkmcnt(1)
	v_mov_b32_e32 v152, v235
	v_mov_b32_e32 v153, v236
	v_mov_b32_e32 v235, v237
	v_pk_add_f32 v[234:235], v[152:153], v[234:235]
	v_pk_mul_f32 v[112:113], v[112:113], v[148:149] op_sel_hi:[1,0]
	v_add_f32_e32 v234, v234, v235
	v_fmamk_f32 v234, v234, 0x3a800000, v229
	v_rsq_f32_e32 v140, v234
	ds_read_b128 v[234:237], v154 offset:2816
	v_pk_mul_f32 v[108:109], v[108:109], v[148:149] op_sel_hi:[1,0]
	v_pk_add_f32 v[128:129], v[128:129], 1.0 op_sel_hi:[1,0]
	v_pk_mul_f32 v[108:109], v[108:109], v[112:113]
	v_pk_mul_f32 v[112:113], v[112:113], s[68:69] op_sel_hi:[1,0]
	v_pk_add_f32 v[120:121], v[120:121], 1.0 op_sel_hi:[1,0]
	v_exp_f32_e32 v112, v112
	v_exp_f32_e32 v113, v113
	v_rcp_f32_e32 v128, v128
	v_rcp_f32_e32 v129, v129
	v_rcp_f32_e32 v120, v120
	v_rcp_f32_e32 v121, v121
	s_waitcnt lgkmcnt(1)
	v_mov_b32_e32 v152, v97
	v_mov_b32_e32 v153, v98
	v_mov_b32_e32 v97, v99
	v_pk_add_f32 v[96:97], v[152:153], v[96:97]
	v_pk_add_f32 v[112:113], v[112:113], 1.0 op_sel_hi:[1,0]
	v_add_f32_e32 v96, v96, v97
	v_fmamk_f32 v96, v96, 0x3a800000, v229
	v_pk_mul_f32 v[126:127], v[126:127], v[128:129]
	v_pk_mul_f32 v[116:117], v[116:117], v[120:121]
	v_rcp_f32_e32 v112, v112
	v_rcp_f32_e32 v113, v113
	v_rsq_f32_e32 v138, v96
	v_cvt_pk_bf16_f32 v124, v124, v125
	v_cvt_pk_bf16_f32 v125, v126, v127
	v_cvt_pk_bf16_f32 v126, v116, v117
	v_pk_mul_f32 v[116:117], v[122:123], v[150:151] op_sel_hi:[1,0]
	v_pk_mul_f32 v[118:119], v[118:119], v[150:151] op_sel_hi:[1,0]
	v_pk_mul_f32 v[108:109], v[108:109], v[112:113]
	v_pk_mul_f32 v[118:119], v[116:117], v[118:119]
	v_pk_mul_f32 v[116:117], v[116:117], s[68:69] op_sel_hi:[1,0]
	v_pk_mul_f32 v[112:113], v[114:115], v[148:149] op_sel_hi:[1,0]
	v_exp_f32_e32 v116, v116
	v_exp_f32_e32 v117, v117
	v_pk_mul_f32 v[110:111], v[110:111], v[148:149] op_sel_hi:[1,0]
	v_pk_mul_f32 v[104:105], v[104:105], v[148:149] op_sel_hi:[1,0]
	v_pk_mul_f32 v[100:101], v[100:101], v[148:149] op_sel_hi:[1,0]
	v_pk_mul_f32 v[110:111], v[112:113], v[110:111]
	v_pk_mul_f32 v[112:113], v[112:113], s[68:69] op_sel_hi:[1,0]
	v_pk_mul_f32 v[100:101], v[104:105], v[100:101]
	v_pk_mul_f32 v[104:105], v[104:105], s[68:69] op_sel_hi:[1,0]
	v_exp_f32_e32 v112, v112
	v_exp_f32_e32 v113, v113
	v_exp_f32_e32 v104, v104
	v_exp_f32_e32 v105, v105
	v_pk_add_f32 v[116:117], v[116:117], 1.0 op_sel_hi:[1,0]
	v_pk_mul_f32 v[92:93], v[92:93], v[146:147] op_sel_hi:[1,0]
	v_rcp_f32_e32 v116, v116
	v_rcp_f32_e32 v117, v117
	v_pk_mul_f32 v[88:89], v[88:89], v[146:147] op_sel_hi:[1,0]
	v_pk_add_f32 v[112:113], v[112:113], 1.0 op_sel_hi:[1,0]
	v_pk_mul_f32 v[88:89], v[88:89], v[92:93]
	v_pk_mul_f32 v[92:93], v[92:93], s[68:69] op_sel_hi:[1,0]
	v_pk_add_f32 v[104:105], v[104:105], 1.0 op_sel_hi:[1,0]
	v_exp_f32_e32 v92, v92
	v_exp_f32_e32 v93, v93
	v_rcp_f32_e32 v112, v112
	v_rcp_f32_e32 v113, v113
	v_rcp_f32_e32 v104, v104
	v_rcp_f32_e32 v105, v105
	v_lshl_or_b32 v152, s1, 7, v147
	v_pk_mul_f32 v[116:117], v[118:119], v[116:117]
	v_ashrrev_i32_e32 v153, 31, v152
	v_cvt_pk_bf16_f32 v127, v116, v117
	v_mov_b64_e32 v[116:117], s[8:9]
	v_mad_i64_i32 v[120:121], s[0:1], v151, s42, v[116:117]
	v_lshlrev_b64 v[118:119], 1, v[152:153]
	v_pk_add_f32 v[92:93], v[92:93], 1.0 op_sel_hi:[1,0]
	v_lshl_add_u64 v[120:121], v[120:121], 0, v[118:119]
	v_pk_mul_f32 v[110:111], v[110:111], v[112:113]
	v_pk_mul_f32 v[100:101], v[100:101], v[104:105]
	v_rcp_f32_e32 v92, v92
	v_rcp_f32_e32 v93, v93
	global_store_dwordx4 v[120:121], v[124:127], off
	v_cvt_pk_bf16_f32 v108, v108, v109
	v_cvt_pk_bf16_f32 v109, v110, v111
	v_cvt_pk_bf16_f32 v110, v100, v101
	v_pk_mul_f32 v[100:101], v[106:107], v[148:149] op_sel_hi:[1,0]
	v_pk_mul_f32 v[102:103], v[102:103], v[148:149] op_sel_hi:[1,0]
	v_pk_mul_f32 v[88:89], v[88:89], v[92:93]
	v_pk_mul_f32 v[102:103], v[100:101], v[102:103]
	v_pk_mul_f32 v[100:101], v[100:101], s[68:69] op_sel_hi:[1,0]
	v_pk_mul_f32 v[92:93], v[94:95], v[146:147] op_sel_hi:[1,0]
	v_exp_f32_e32 v100, v100
	v_exp_f32_e32 v101, v101
	v_pk_mul_f32 v[90:91], v[90:91], v[146:147] op_sel_hi:[1,0]
	v_pk_mul_f32 v[84:85], v[84:85], v[146:147] op_sel_hi:[1,0]
	v_pk_mul_f32 v[80:81], v[80:81], v[146:147] op_sel_hi:[1,0]
	v_pk_mul_f32 v[90:91], v[92:93], v[90:91]
	v_pk_mul_f32 v[92:93], v[92:93], s[68:69] op_sel_hi:[1,0]
	v_pk_mul_f32 v[80:81], v[84:85], v[80:81]
	v_pk_mul_f32 v[84:85], v[84:85], s[68:69] op_sel_hi:[1,0]
	v_exp_f32_e32 v92, v92
	v_exp_f32_e32 v93, v93
	v_exp_f32_e32 v84, v84
	v_exp_f32_e32 v85, v85
	v_pk_add_f32 v[100:101], v[100:101], 1.0 op_sel_hi:[1,0]
	v_pk_mul_f32 v[76:77], v[76:77], v[144:145] op_sel_hi:[1,0]
	v_rcp_f32_e32 v100, v100
	v_rcp_f32_e32 v101, v101
	v_pk_mul_f32 v[72:73], v[72:73], v[144:145] op_sel_hi:[1,0]
	v_pk_add_f32 v[92:93], v[92:93], 1.0 op_sel_hi:[1,0]
	v_pk_mul_f32 v[72:73], v[72:73], v[76:77]
	v_pk_mul_f32 v[76:77], v[76:77], s[68:69] op_sel_hi:[1,0]
	v_pk_add_f32 v[84:85], v[84:85], 1.0 op_sel_hi:[1,0]
	v_exp_f32_e32 v76, v76
	v_exp_f32_e32 v77, v77
	v_rcp_f32_e32 v92, v92
	v_rcp_f32_e32 v93, v93
	v_rcp_f32_e32 v84, v84
	v_rcp_f32_e32 v85, v85
	v_pk_mul_f32 v[100:101], v[102:103], v[100:101]
	v_pk_add_f32 v[76:77], v[76:77], 1.0 op_sel_hi:[1,0]
	v_cvt_pk_bf16_f32 v111, v100, v101
	v_or_b32_e32 v100, 16, v151
	v_mad_i64_i32 v[100:101], s[0:1], v100, s42, v[116:117]
	v_lshl_add_u64 v[100:101], v[100:101], 0, v[118:119]
	v_pk_mul_f32 v[90:91], v[90:91], v[92:93]
	v_pk_mul_f32 v[80:81], v[80:81], v[84:85]
	v_rcp_f32_e32 v76, v76
	v_rcp_f32_e32 v77, v77
	global_store_dwordx4 v[100:101], v[108:111], off
	v_cvt_pk_bf16_f32 v88, v88, v89
	v_cvt_pk_bf16_f32 v89, v90, v91
	v_cvt_pk_bf16_f32 v90, v80, v81
	v_pk_mul_f32 v[80:81], v[86:87], v[146:147] op_sel_hi:[1,0]
	v_pk_mul_f32 v[82:83], v[82:83], v[146:147] op_sel_hi:[1,0]
	v_pk_mul_f32 v[72:73], v[72:73], v[76:77]
	v_pk_mul_f32 v[82:83], v[80:81], v[82:83]
	v_pk_mul_f32 v[80:81], v[80:81], s[68:69] op_sel_hi:[1,0]
	v_pk_mul_f32 v[76:77], v[78:79], v[144:145] op_sel_hi:[1,0]
	v_exp_f32_e32 v80, v80
	v_exp_f32_e32 v81, v81
	v_pk_mul_f32 v[74:75], v[74:75], v[144:145] op_sel_hi:[1,0]
	v_pk_mul_f32 v[68:69], v[68:69], v[144:145] op_sel_hi:[1,0]
	v_pk_mul_f32 v[64:65], v[64:65], v[144:145] op_sel_hi:[1,0]
	v_pk_mul_f32 v[74:75], v[76:77], v[74:75]
	v_pk_mul_f32 v[76:77], v[76:77], s[68:69] op_sel_hi:[1,0]
	v_pk_mul_f32 v[64:65], v[68:69], v[64:65]
	v_pk_mul_f32 v[68:69], v[68:69], s[68:69] op_sel_hi:[1,0]
	v_exp_f32_e32 v76, v76
	v_exp_f32_e32 v77, v77
	v_exp_f32_e32 v68, v68
	v_exp_f32_e32 v69, v69
	v_pk_add_f32 v[80:81], v[80:81], 1.0 op_sel_hi:[1,0]
	v_pk_add_f32 v[76:77], v[76:77], 1.0 op_sel_hi:[1,0]
	v_rcp_f32_e32 v80, v80
	v_rcp_f32_e32 v81, v81
	v_pk_add_f32 v[68:69], v[68:69], 1.0 op_sel_hi:[1,0]
	v_rcp_f32_e32 v76, v76
	v_rcp_f32_e32 v77, v77
	v_rcp_f32_e32 v68, v68
	v_rcp_f32_e32 v69, v69
	v_pk_mul_f32 v[80:81], v[82:83], v[80:81]
	v_pk_mul_f32 v[74:75], v[74:75], v[76:77]
	v_cvt_pk_bf16_f32 v91, v80, v81
	v_or_b32_e32 v80, 32, v151
	v_mad_i64_i32 v[80:81], s[0:1], v80, s42, v[116:117]
	v_lshl_add_u64 v[80:81], v[80:81], 0, v[118:119]
	v_pk_mul_f32 v[64:65], v[64:65], v[68:69]
	global_store_dwordx4 v[80:81], v[88:91], off
	v_cvt_pk_bf16_f32 v72, v72, v73
	v_cvt_pk_bf16_f32 v73, v74, v75
	v_cvt_pk_bf16_f32 v74, v64, v65
	v_pk_mul_f32 v[64:65], v[70:71], v[144:145] op_sel_hi:[1,0]
	v_pk_mul_f32 v[66:67], v[66:67], v[144:145] op_sel_hi:[1,0]
	s_nop 0
	v_pk_mul_f32 v[66:67], v[64:65], v[66:67]
	v_pk_mul_f32 v[64:65], v[64:65], s[68:69] op_sel_hi:[1,0]
	s_nop 0
	v_exp_f32_e32 v64, v64
	v_exp_f32_e32 v65, v65
	s_nop 0
	v_pk_add_f32 v[64:65], v[64:65], 1.0 op_sel_hi:[1,0]
	s_nop 0
	v_rcp_f32_e32 v64, v64
	v_rcp_f32_e32 v65, v65
	s_nop 0
	v_pk_mul_f32 v[64:65], v[66:67], v[64:65]
	s_nop 0
	v_cvt_pk_bf16_f32 v75, v64, v65
	v_or_b32_e32 v64, 48, v151
	v_mad_i64_i32 v[64:65], s[0:1], v64, s42, v[116:117]
	v_lshl_add_u64 v[64:65], v[64:65], 0, v[118:119]
	global_store_dwordx4 v[64:65], v[72:75], off
	v_add_u32_e32 v64, 0x80, v151
	v_pk_mul_f32 v[60:61], v[60:61], v[142:143] op_sel_hi:[1,0]
	v_pk_mul_f32 v[56:57], v[56:57], v[142:143] op_sel_hi:[1,0]
	v_pk_mul_f32 v[58:59], v[58:59], v[142:143] op_sel_hi:[1,0]
	v_pk_mul_f32 v[56:57], v[60:61], v[56:57]
	v_pk_mul_f32 v[60:61], v[60:61], s[68:69] op_sel_hi:[1,0]
	v_pk_mul_f32 v[52:53], v[52:53], v[142:143] op_sel_hi:[1,0]
	v_exp_f32_e32 v60, v60
	v_exp_f32_e32 v61, v61
	v_pk_mul_f32 v[48:49], v[48:49], v[142:143] op_sel_hi:[1,0]
	v_pk_mul_f32 v[44:45], v[44:45], v[140:141] op_sel_hi:[1,0]
	v_pk_mul_f32 v[48:49], v[52:53], v[48:49]
	v_pk_add_f32 v[60:61], v[60:61], 1.0 op_sel_hi:[1,0]
	v_pk_mul_f32 v[52:53], v[52:53], s[68:69] op_sel_hi:[1,0]
	v_rcp_f32_e32 v60, v60
	v_rcp_f32_e32 v61, v61
	v_exp_f32_e32 v52, v52
	v_exp_f32_e32 v53, v53
	v_pk_mul_f32 v[40:41], v[40:41], v[140:141] op_sel_hi:[1,0]
	v_pk_mul_f32 v[56:57], v[56:57], v[60:61]
	v_pk_mul_f32 v[60:61], v[62:63], v[142:143] op_sel_hi:[1,0]
	v_pk_mul_f32 v[40:41], v[40:41], v[44:45]
	v_pk_mul_f32 v[58:59], v[60:61], v[58:59]
	v_pk_mul_f32 v[60:61], v[60:61], s[68:69] op_sel_hi:[1,0]
	v_pk_mul_f32 v[44:45], v[44:45], s[68:69] op_sel_hi:[1,0]
	v_exp_f32_e32 v60, v60
	v_exp_f32_e32 v61, v61
	v_exp_f32_e32 v44, v44
	v_exp_f32_e32 v45, v45
	v_pk_add_f32 v[52:53], v[52:53], 1.0 op_sel_hi:[1,0]
	v_pk_add_f32 v[60:61], v[60:61], 1.0 op_sel_hi:[1,0]
	v_rcp_f32_e32 v52, v52
	v_rcp_f32_e32 v60, v60
	v_rcp_f32_e32 v61, v61
	v_rcp_f32_e32 v53, v53
	v_pk_add_f32 v[44:45], v[44:45], 1.0 op_sel_hi:[1,0]
	v_cvt_pk_bf16_f32 v56, v56, v57
	v_pk_mul_f32 v[58:59], v[58:59], v[60:61]
	v_rcp_f32_e32 v44, v44
	v_rcp_f32_e32 v45, v45
	v_pk_mul_f32 v[48:49], v[48:49], v[52:53]
	v_cvt_pk_bf16_f32 v57, v58, v59
	v_pk_mul_f32 v[50:51], v[50:51], v[142:143] op_sel_hi:[1,0]
	v_cvt_pk_bf16_f32 v58, v48, v49
	v_pk_mul_f32 v[48:49], v[54:55], v[142:143] op_sel_hi:[1,0]
	v_pk_mul_f32 v[40:41], v[40:41], v[44:45]
	v_pk_mul_f32 v[50:51], v[48:49], v[50:51]
	v_pk_mul_f32 v[48:49], v[48:49], s[68:69] op_sel_hi:[1,0]
	v_pk_mul_f32 v[44:45], v[46:47], v[140:141] op_sel_hi:[1,0]
	v_exp_f32_e32 v48, v48
	v_exp_f32_e32 v49, v49
	v_pk_mul_f32 v[42:43], v[42:43], v[140:141] op_sel_hi:[1,0]
	v_pk_mul_f32 v[36:37], v[36:37], v[140:141] op_sel_hi:[1,0]
	v_pk_mul_f32 v[32:33], v[32:33], v[140:141] op_sel_hi:[1,0]
	v_pk_mul_f32 v[42:43], v[44:45], v[42:43]
	v_pk_mul_f32 v[44:45], v[44:45], s[68:69] op_sel_hi:[1,0]
	v_pk_mul_f32 v[32:33], v[36:37], v[32:33]
	v_pk_mul_f32 v[36:37], v[36:37], s[68:69] op_sel_hi:[1,0]
	v_exp_f32_e32 v44, v44
	v_exp_f32_e32 v45, v45
	v_exp_f32_e32 v36, v36
	v_exp_f32_e32 v37, v37
	v_pk_add_f32 v[48:49], v[48:49], 1.0 op_sel_hi:[1,0]
	v_pk_mul_f32 v[28:29], v[28:29], v[138:139] op_sel_hi:[1,0]
	v_pk_mul_f32 v[24:25], v[24:25], v[138:139] op_sel_hi:[1,0]
	v_rcp_f32_e32 v48, v48
	v_rcp_f32_e32 v49, v49
	v_pk_mul_f32 v[24:25], v[24:25], v[28:29]
	v_pk_mul_f32 v[28:29], v[28:29], s[68:69] op_sel_hi:[1,0]
	v_pk_add_f32 v[44:45], v[44:45], 1.0 op_sel_hi:[1,0]
	v_pk_add_f32 v[36:37], v[36:37], 1.0 op_sel_hi:[1,0]
	v_exp_f32_e32 v28, v28
	v_exp_f32_e32 v29, v29
	v_rcp_f32_e32 v44, v44
	v_rcp_f32_e32 v45, v45
	v_rcp_f32_e32 v36, v36
	v_rcp_f32_e32 v37, v37
	v_pk_mul_f32 v[48:49], v[50:51], v[48:49]
	v_pk_add_f32 v[28:29], v[28:29], 1.0 op_sel_hi:[1,0]
	v_cvt_pk_bf16_f32 v59, v48, v49
	v_mad_i64_i32 v[48:49], s[0:1], v64, s42, v[116:117]
	v_lshl_add_u64 v[48:49], v[48:49], 0, v[118:119]
	v_pk_mul_f32 v[42:43], v[42:43], v[44:45]
	v_pk_mul_f32 v[32:33], v[32:33], v[36:37]
	v_rcp_f32_e32 v28, v28
	v_rcp_f32_e32 v29, v29
	global_store_dwordx4 v[48:49], v[56:59], off
	v_cvt_pk_bf16_f32 v40, v40, v41
	v_cvt_pk_bf16_f32 v41, v42, v43
	v_cvt_pk_bf16_f32 v42, v32, v33
	v_pk_mul_f32 v[32:33], v[38:39], v[140:141] op_sel_hi:[1,0]
	v_pk_mul_f32 v[34:35], v[34:35], v[140:141] op_sel_hi:[1,0]
	v_pk_mul_f32 v[24:25], v[24:25], v[28:29]
	v_pk_mul_f32 v[34:35], v[32:33], v[34:35]
	v_pk_mul_f32 v[32:33], v[32:33], s[68:69] op_sel_hi:[1,0]
	v_pk_mul_f32 v[28:29], v[30:31], v[138:139] op_sel_hi:[1,0]
	v_exp_f32_e32 v32, v32
	v_exp_f32_e32 v33, v33
	v_pk_mul_f32 v[26:27], v[26:27], v[138:139] op_sel_hi:[1,0]
	v_pk_mul_f32 v[20:21], v[20:21], v[138:139] op_sel_hi:[1,0]
	v_pk_mul_f32 v[16:17], v[16:17], v[138:139] op_sel_hi:[1,0]
	v_pk_mul_f32 v[26:27], v[28:29], v[26:27]
	v_pk_mul_f32 v[28:29], v[28:29], s[68:69] op_sel_hi:[1,0]
	v_pk_mul_f32 v[16:17], v[20:21], v[16:17]
	v_pk_mul_f32 v[20:21], v[20:21], s[68:69] op_sel_hi:[1,0]
	v_exp_f32_e32 v28, v28
	v_exp_f32_e32 v29, v29
	v_exp_f32_e32 v20, v20
	v_exp_f32_e32 v21, v21
	v_pk_add_f32 v[32:33], v[32:33], 1.0 op_sel_hi:[1,0]
	v_pk_add_f32 v[28:29], v[28:29], 1.0 op_sel_hi:[1,0]
	v_rcp_f32_e32 v32, v32
	v_rcp_f32_e32 v33, v33
	v_pk_add_f32 v[20:21], v[20:21], 1.0 op_sel_hi:[1,0]
	v_rcp_f32_e32 v28, v28
	v_rcp_f32_e32 v29, v29
	v_rcp_f32_e32 v20, v20
	v_rcp_f32_e32 v21, v21
	v_pk_mul_f32 v[32:33], v[34:35], v[32:33]
	v_pk_mul_f32 v[26:27], v[26:27], v[28:29]
	v_cvt_pk_bf16_f32 v43, v32, v33
	v_add_u32_e32 v32, 0x90, v151
	v_mad_i64_i32 v[32:33], s[0:1], v32, s42, v[116:117]
	v_lshl_add_u64 v[32:33], v[32:33], 0, v[118:119]
	v_pk_mul_f32 v[16:17], v[16:17], v[20:21]
	global_store_dwordx4 v[32:33], v[40:43], off
	v_cvt_pk_bf16_f32 v24, v24, v25
	v_cvt_pk_bf16_f32 v25, v26, v27
	v_cvt_pk_bf16_f32 v26, v16, v17
	v_pk_mul_f32 v[16:17], v[22:23], v[138:139] op_sel_hi:[1,0]
	v_pk_mul_f32 v[18:19], v[18:19], v[138:139] op_sel_hi:[1,0]
	s_mov_b64 s[24:25], -1
	v_pk_mul_f32 v[18:19], v[16:17], v[18:19]
	v_pk_mul_f32 v[16:17], v[16:17], s[68:69] op_sel_hi:[1,0]
	s_andn2_b64 vcc, exec, s[4:5]
	v_exp_f32_e32 v16, v16
	v_exp_f32_e32 v17, v17
	s_nop 0
	v_pk_add_f32 v[16:17], v[16:17], 1.0 op_sel_hi:[1,0]
	s_nop 0
	v_rcp_f32_e32 v16, v16
	v_rcp_f32_e32 v17, v17
	s_nop 0
	v_pk_mul_f32 v[16:17], v[18:19], v[16:17]
	s_nop 0
	v_cvt_pk_bf16_f32 v27, v16, v17
	v_add_u32_e32 v16, 0xa0, v151
	v_mad_i64_i32 v[16:17], s[0:1], v16, s42, v[116:117]
	v_lshl_add_u64 v[16:17], v[16:17], 0, v[118:119]
	global_store_dwordx4 v[16:17], v[24:27], off
	s_waitcnt lgkmcnt(0)
	v_mov_b32_e32 v16, v235
	v_mov_b32_e32 v17, v236
	v_mov_b32_e32 v235, v237
	v_pk_add_f32 v[16:17], v[16:17], v[234:235]
	s_nop 0
	v_add_f32_e32 v16, v16, v17
	v_fmamk_f32 v16, v16, 0x3a800000, v229
	v_rsq_f32_e32 v16, v16
	s_nop 0
	v_pk_mul_f32 v[12:13], v[12:13], v[16:17] op_sel_hi:[1,0]
	v_pk_mul_f32 v[8:9], v[8:9], v[16:17] op_sel_hi:[1,0]
	v_pk_mul_f32 v[10:11], v[10:11], v[16:17] op_sel_hi:[1,0]
	v_pk_mul_f32 v[8:9], v[8:9], v[12:13]
	v_pk_mul_f32 v[12:13], v[12:13], s[68:69] op_sel_hi:[1,0]
	v_pk_mul_f32 v[4:5], v[4:5], v[16:17] op_sel_hi:[1,0]
	v_exp_f32_e32 v12, v12
	v_exp_f32_e32 v13, v13
	v_pk_mul_f32 v[0:1], v[0:1], v[16:17] op_sel_hi:[1,0]
	v_pk_mul_f32 v[2:3], v[2:3], v[16:17] op_sel_hi:[1,0]
	v_pk_mul_f32 v[0:1], v[4:5], v[0:1]
	v_pk_add_f32 v[12:13], v[12:13], 1.0 op_sel_hi:[1,0]
	v_pk_mul_f32 v[4:5], v[4:5], s[68:69] op_sel_hi:[1,0]
	v_rcp_f32_e32 v12, v12
	v_rcp_f32_e32 v13, v13
	v_exp_f32_e32 v4, v4
	v_exp_f32_e32 v5, v5
	v_pk_mul_f32 v[8:9], v[8:9], v[12:13]
	v_pk_mul_f32 v[12:13], v[14:15], v[16:17] op_sel_hi:[1,0]
	v_pk_add_f32 v[4:5], v[4:5], 1.0 op_sel_hi:[1,0]
	v_pk_mul_f32 v[10:11], v[12:13], v[10:11]
	v_pk_mul_f32 v[12:13], v[12:13], s[68:69] op_sel_hi:[1,0]
	v_rcp_f32_e32 v4, v4
	v_exp_f32_e32 v12, v12
	v_exp_f32_e32 v13, v13
	v_rcp_f32_e32 v5, v5
	v_cvt_pk_bf16_f32 v8, v8, v9
	v_pk_add_f32 v[12:13], v[12:13], 1.0 op_sel_hi:[1,0]
	s_nop 0
	v_rcp_f32_e32 v12, v12
	v_rcp_f32_e32 v13, v13
	v_pk_mul_f32 v[0:1], v[0:1], v[4:5]
	v_pk_mul_f32 v[10:11], v[10:11], v[12:13]
	s_nop 0
	v_cvt_pk_bf16_f32 v9, v10, v11
	v_cvt_pk_bf16_f32 v10, v0, v1
	v_pk_mul_f32 v[0:1], v[6:7], v[16:17] op_sel_hi:[1,0]
	s_nop 0
	v_pk_mul_f32 v[2:3], v[0:1], v[2:3]
	v_pk_mul_f32 v[0:1], v[0:1], s[68:69] op_sel_hi:[1,0]
	s_nop 0
	v_exp_f32_e32 v0, v0
	v_exp_f32_e32 v1, v1
	s_nop 0
	v_pk_add_f32 v[0:1], v[0:1], 1.0 op_sel_hi:[1,0]
	s_nop 0
	v_rcp_f32_e32 v0, v0
	v_rcp_f32_e32 v1, v1
	s_nop 0
	v_pk_mul_f32 v[0:1], v[2:3], v[0:1]
	s_nop 0
	v_cvt_pk_bf16_f32 v11, v0, v1
	v_add_u32_e32 v0, 0xb0, v151
	v_mad_i64_i32 v[0:1], s[0:1], v0, s42, v[116:117]
	v_lshl_add_u64 v[0:1], v[0:1], 0, v[118:119]
	global_store_dwordx4 v[0:1], v[8:11], off
	s_cbranch_vccnz .LBB0_522
	s_andn2_b64 vcc, exec, s[6:7]
	s_cbranch_vccnz .LBB0_521
	s_barrier
	s_branch .LBB0_521
